# NSA2 epilogues: second sub-block's previous-O rows requested as 4 dwordx4 (was 8 dwordx2) with half-wave exchange
# baseline (speedup 1.0000x reference)
.LBB0_625:
	global_load_ushort v0, v[154:155], off offset:2820
	global_load_dwordx2 v[66:67], v[146:147], off
	global_load_dwordx2 v[68:69], v[146:147], off offset:64
	global_load_dwordx2 v[70:71], v[146:147], off offset:16
	global_load_dwordx2 v[72:73], v[146:147], off offset:80
	global_load_dwordx2 v[74:75], v[146:147], off offset:32
	global_load_dwordx2 v[76:77], v[146:147], off offset:96
	global_load_dwordx2 v[78:79], v[146:147], off offset:48
	global_load_dwordx2 v[80:81], v[146:147], off offset:112
	v_and_b32_e32 v230, 32, v200
	v_lshrrev_b32_e32 v230, 2, v230
	v_mov_b32_e32 v231, 0
	v_lshl_add_u64 v[230:231], v[148:149], 0, v[230:231]
	global_load_dwordx4 v[206:209], v[230:231], off
	global_load_dwordx4 v[210:213], v[230:231], off offset:32
	global_load_dwordx4 v[214:217], v[230:231], off offset:64
	global_load_dwordx4 v[218:221], v[230:231], off offset:96
	global_load_ushort v224, v[152:153], off offset:2820
	ds_bpermute_b32 v82, v166, v151
	s_waitcnt lgkmcnt(0)
	v_add_f32_e32 v82, v151, v82
	v_max_f32_e32 v82, 0xda24260, v82
	v_div_scale_f32 v83, s[0:1], v82, v82, 1.0
	v_rcp_f32_e32 v84, v83
	v_div_scale_f32 v85, s[2:3], 1.0, v82, 1.0
	v_fma_f32 v86, -v83, v84, 1.0
	v_fmac_f32_e32 v84, v86, v84
	v_mul_f32_e32 v86, v85, v84
	v_fma_f32 v87, -v83, v86, v85
	v_fmac_f32_e32 v86, v87, v84
	v_fma_f32 v83, -v83, v86, v85
	s_waitcnt vmcnt(8)
	v_lshlrev_b32_e32 v0, 16, v0
	v_mul_f32_e32 v0, 0xbfb8aa3b, v0
	v_exp_f32_e32 v0, v0
	s_waitcnt vmcnt(7)
	v_lshlrev_b32_e32 v85, 16, v66
	v_and_b32_e32 v66, 0xffff0000, v66
	v_lshlrev_b32_e32 v87, 16, v67
	v_add_f32_e32 v0, 1.0, v0
	v_div_scale_f32 v100, s[0:1], v0, v0, 1.0
	v_rcp_f32_e32 v101, v100
	v_div_scale_f32 v103, vcc, 1.0, v0, 1.0
	v_and_b32_e32 v67, 0xffff0000, v67
	v_fma_f32 v104, -v100, v101, 1.0
	v_fmac_f32_e32 v101, v104, v101
	v_mul_f32_e32 v104, v103, v101
	v_fma_f32 v105, -v100, v104, v103
	v_fmac_f32_e32 v104, v105, v101
	v_fma_f32 v100, -v100, v104, v103
	v_div_fmas_f32 v100, v100, v101, v104
	s_mov_b64 vcc, s[2:3]
	v_div_fmas_f32 v83, v83, v84, v86
	v_div_fixup_f32 v0, v100, v0, 1.0
	v_div_fixup_f32 v82, v83, v82, 1.0
	s_waitcnt vmcnt(6)
	v_lshlrev_b32_e32 v88, 16, v68
	v_and_b32_e32 v68, 0xffff0000, v68
	v_mul_f32_e32 v0, v82, v0
	v_lshlrev_b32_e32 v89, 16, v69
	v_and_b32_e32 v69, 0xffff0000, v69
	s_waitcnt vmcnt(5)
	v_lshlrev_b32_e32 v90, 16, v70
	v_and_b32_e32 v70, 0xffff0000, v70
	v_lshlrev_b32_e32 v91, 16, v71
	v_and_b32_e32 v71, 0xffff0000, v71
	v_fmac_f32_e32 v85, v50, v0
	v_fmac_f32_e32 v66, v51, v0
	v_fmac_f32_e32 v87, v52, v0
	v_fmac_f32_e32 v67, v53, v0
	v_fmac_f32_e32 v88, v34, v0
	v_fmac_f32_e32 v68, v35, v0
	v_cvt_pk_bf16_f32 v232, v85, v66
	v_cvt_pk_bf16_f32 v233, v87, v67
	s_waitcnt vmcnt(4)
	v_lshlrev_b32_e32 v92, 16, v72
	v_and_b32_e32 v72, 0xffff0000, v72
	v_lshlrev_b32_e32 v93, 16, v73
	v_and_b32_e32 v73, 0xffff0000, v73
	s_waitcnt vmcnt(3)
	v_lshlrev_b32_e32 v94, 16, v74
	v_and_b32_e32 v74, 0xffff0000, v74
	v_lshlrev_b32_e32 v95, 16, v75
	v_and_b32_e32 v75, 0xffff0000, v75
	v_fmac_f32_e32 v89, v36, v0
	v_fmac_f32_e32 v69, v37, v0
	v_fmac_f32_e32 v90, v54, v0
	v_fmac_f32_e32 v70, v55, v0
	v_fmac_f32_e32 v91, v56, v0
	v_fmac_f32_e32 v71, v57, v0
	v_cvt_pk_bf16_f32 v240, v88, v68
	v_cvt_pk_bf16_f32 v241, v89, v69
	s_nop 0
	s_nop 0
	v_cvt_pk_bf16_f32 v234, v90, v70
	v_cvt_pk_bf16_f32 v235, v91, v71
	s_waitcnt vmcnt(2)
	v_lshlrev_b32_e32 v96, 16, v76
	v_and_b32_e32 v76, 0xffff0000, v76
	v_lshlrev_b32_e32 v97, 16, v77
	v_and_b32_e32 v77, 0xffff0000, v77
	s_waitcnt vmcnt(1)
	v_lshlrev_b32_e32 v98, 16, v78
	v_and_b32_e32 v78, 0xffff0000, v78
	v_lshlrev_b32_e32 v99, 16, v79
	v_and_b32_e32 v79, 0xffff0000, v79
	v_fmac_f32_e32 v92, v38, v0
	v_fmac_f32_e32 v72, v39, v0
	v_fmac_f32_e32 v93, v40, v0
	v_fmac_f32_e32 v73, v41, v0
	v_fmac_f32_e32 v94, v58, v0
	v_fmac_f32_e32 v74, v59, v0
	v_fmac_f32_e32 v95, v60, v0
	v_fmac_f32_e32 v75, v61, v0
	s_waitcnt vmcnt(0)
	v_and_b32_e32 v38, 0xffff0000, v80
	v_lshlrev_b32_e32 v39, 16, v81
	v_and_b32_e32 v40, 0xffff0000, v81
	v_cvt_pk_bf16_f32 v242, v92, v72
	v_cvt_pk_bf16_f32 v243, v93, v73
	v_and_b32_e32 v248, 32, v200
	v_lshrrev_b32_e32 v248, 2, v248
	v_mov_b32_e32 v249, 0
	v_lshl_add_u64 v[248:249], v[146:147], 0, v[248:249]
	v_permlane32_swap_b32_e32 v232, v234
	v_permlane32_swap_b32_e32 v233, v235
	global_store_dwordx4 v[248:249], v[232:235], off
	s_nop 1
	v_permlane32_swap_b32_e32 v240, v242
	v_permlane32_swap_b32_e32 v241, v243
	global_store_dwordx4 v[248:249], v[240:243], off offset:64
	v_cvt_pk_bf16_f32 v236, v94, v74
	v_cvt_pk_bf16_f32 v237, v95, v75
	v_lshlrev_b32_e32 v102, 16, v80
	v_fmac_f32_e32 v96, v42, v0
	v_fmac_f32_e32 v76, v43, v0
	v_fmac_f32_e32 v97, v44, v0
	v_fmac_f32_e32 v77, v45, v0
	v_fmac_f32_e32 v98, v62, v0
	v_fmac_f32_e32 v78, v63, v0
	v_fmac_f32_e32 v99, v64, v0
	v_fmac_f32_e32 v79, v65, v0
	v_fmac_f32_e32 v38, v47, v0
	v_fmac_f32_e32 v39, v48, v0
	v_fmac_f32_e32 v40, v49, v0
	v_cvt_pk_bf16_f32 v244, v96, v76
	v_cvt_pk_bf16_f32 v245, v97, v77
	s_nop 0
	s_nop 0
	v_cvt_pk_bf16_f32 v238, v98, v78
	v_cvt_pk_bf16_f32 v239, v99, v79
	v_fmac_f32_e32 v102, v46, v0
	v_cvt_pk_bf16_f32 v246, v102, v38
	v_cvt_pk_bf16_f32 v247, v39, v40
	s_waitcnt vmcnt(2)
	v_permlane32_swap_b32_e32 v206, v208
	v_permlane32_swap_b32_e32 v207, v209
	v_permlane32_swap_b32_e32 v210, v212
	v_permlane32_swap_b32_e32 v211, v213
	v_permlane32_swap_b32_e32 v214, v216
	v_permlane32_swap_b32_e32 v215, v217
	v_permlane32_swap_b32_e32 v218, v220
	v_permlane32_swap_b32_e32 v219, v221
	v_mov_b64_e32 v[38:39], v[214:215]
	v_mov_b64_e32 v[40:41], v[216:217]
	s_nop 0
	v_permlane32_swap_b32_e32 v236, v238
	v_permlane32_swap_b32_e32 v237, v239
	global_store_dwordx4 v[248:249], v[236:239], off offset:32
	v_permlane32_swap_b32_e32 v244, v246
	v_permlane32_swap_b32_e32 v245, v247
	global_store_dwordx4 v[248:249], v[244:247], off offset:96
	v_mov_b32_e32 v0, v224
	s_nop 0
	v_mov_b64_e32 v[34:35], v[206:207]
	v_mov_b64_e32 v[36:37], v[208:209]
	v_mov_b64_e32 v[42:43], v[210:211]
	ds_bpermute_b32 v46, v166, v150
	v_mov_b64_e32 v[44:45], v[218:219]
	s_waitcnt lgkmcnt(0)
	v_add_f32_e32 v46, v150, v46
	v_max_f32_e32 v50, 0xda24260, v46
	v_div_scale_f32 v51, s[0:1], v50, v50, 1.0
	v_rcp_f32_e32 v52, v51
	v_div_scale_f32 v53, s[2:3], 1.0, v50, 1.0
	v_fma_f32 v48, -v51, v52, 1.0
	v_fmac_f32_e32 v52, v48, v52
	v_mul_f32_e32 v54, v53, v52
	v_fma_f32 v48, -v51, v54, v53
	v_fmac_f32_e32 v54, v48, v52
	v_mov_b64_e32 v[48:49], v[220:221]
	v_mov_b64_e32 v[46:47], v[212:213]
	v_fma_f32 v51, -v51, v54, v53
	s_nop 0
	v_lshlrev_b32_e32 v0, 16, v0
	v_mul_f32_e32 v0, 0xbfb8aa3b, v0
	v_exp_f32_e32 v0, v0
	s_nop 0
	v_lshlrev_b32_e32 v61, 16, v37
	v_lshlrev_b32_e32 v58, 16, v34
	v_and_b32_e32 v34, 0xffff0000, v34
	v_add_f32_e32 v0, 1.0, v0
	v_div_scale_f32 v62, s[0:1], v0, v0, 1.0
	v_rcp_f32_e32 v63, v62
	v_div_scale_f32 v65, vcc, 1.0, v0, 1.0
	v_lshlrev_b32_e32 v59, 16, v35
	v_fma_f32 v66, -v62, v63, 1.0
	v_fmac_f32_e32 v63, v66, v63
	v_mul_f32_e32 v66, v65, v63
	v_fma_f32 v67, -v62, v66, v65
	v_fmac_f32_e32 v66, v67, v63
	v_fma_f32 v62, -v62, v66, v65
	v_div_fmas_f32 v62, v62, v63, v66
	s_mov_b64 vcc, s[2:3]
	v_div_fmas_f32 v51, v51, v52, v54
	v_div_fixup_f32 v0, v62, v0, 1.0
	v_div_fixup_f32 v50, v51, v50, 1.0
	v_mul_f32_e32 v0, v50, v0
	v_fmac_f32_e32 v61, v8, v0
	s_nop 0
	v_and_b32_e32 v8, 0xffff0000, v43
	v_and_b32_e32 v35, 0xffff0000, v35
	v_fmac_f32_e32 v8, v13, v0
	s_nop 0
	v_lshlrev_b32_e32 v13, 16, v46
	v_lshlrev_b32_e32 v53, 16, v38
	v_and_b32_e32 v38, 0xffff0000, v38
	v_lshlrev_b32_e32 v55, 16, v39
	v_and_b32_e32 v39, 0xffff0000, v39
	v_lshlrev_b32_e32 v60, 16, v36
	v_and_b32_e32 v36, 0xffff0000, v36
	v_and_b32_e32 v37, 0xffff0000, v37
	v_fmac_f32_e32 v58, v2, v0
	v_fmac_f32_e32 v34, v3, v0
	v_fmac_f32_e32 v59, v4, v0
	v_fmac_f32_e32 v35, v5, v0
	v_fmac_f32_e32 v13, v14, v0
	v_and_b32_e32 v14, 0xffff0000, v46
	v_cvt_pk_bf16_f32 v232, v58, v34
	v_cvt_pk_bf16_f32 v233, v59, v35
	v_lshlrev_b32_e32 v56, 16, v40
	v_and_b32_e32 v40, 0xffff0000, v40
	v_lshlrev_b32_e32 v57, 16, v41
	v_and_b32_e32 v41, 0xffff0000, v41
	v_lshlrev_b32_e32 v64, 16, v42
	v_fmac_f32_e32 v53, v18, v0
	v_fmac_f32_e32 v38, v19, v0
	v_fmac_f32_e32 v55, v20, v0
	v_fmac_f32_e32 v39, v21, v0
	v_fmac_f32_e32 v60, v6, v0
	v_fmac_f32_e32 v36, v7, v0
	v_fmac_f32_e32 v37, v9, v0
	v_and_b32_e32 v6, 0xffff0000, v42
	v_lshlrev_b32_e32 v7, 16, v43
	v_fmac_f32_e32 v14, v15, v0
	v_lshlrev_b32_e32 v15, 16, v47
	v_cvt_pk_bf16_f32 v240, v53, v38
	v_cvt_pk_bf16_f32 v241, v55, v39
	s_nop 0
	s_nop 0
	v_cvt_pk_bf16_f32 v234, v60, v36
	v_cvt_pk_bf16_f32 v235, v61, v37
	v_fmac_f32_e32 v56, v22, v0
	v_fmac_f32_e32 v40, v23, v0
	v_fmac_f32_e32 v57, v24, v0
	v_fmac_f32_e32 v41, v25, v0
	v_fmac_f32_e32 v64, v10, v0
	v_fmac_f32_e32 v6, v11, v0
	v_fmac_f32_e32 v7, v12, v0
	v_lshlrev_b32_e32 v9, 16, v44
	v_and_b32_e32 v10, 0xffff0000, v44
	v_lshlrev_b32_e32 v11, 16, v45
	v_and_b32_e32 v12, 0xffff0000, v45
	v_fmac_f32_e32 v15, v16, v0
	v_and_b32_e32 v16, 0xffff0000, v47
	v_cvt_pk_bf16_f32 v242, v56, v40
	v_cvt_pk_bf16_f32 v243, v57, v41
	v_and_b32_e32 v248, 32, v200
	v_lshrrev_b32_e32 v248, 2, v248
	v_mov_b32_e32 v249, 0
	v_lshl_add_u64 v[248:249], v[148:149], 0, v[248:249]
	v_permlane32_swap_b32_e32 v232, v234
	v_permlane32_swap_b32_e32 v233, v235
	global_store_dwordx4 v[248:249], v[232:235], off
	s_nop 1
	v_permlane32_swap_b32_e32 v240, v242
	v_permlane32_swap_b32_e32 v241, v243
	global_store_dwordx4 v[248:249], v[240:243], off offset:64
	v_cvt_pk_bf16_f32 v236, v64, v6
	v_cvt_pk_bf16_f32 v237, v7, v8
	v_fmac_f32_e32 v9, v26, v0
	v_fmac_f32_e32 v10, v27, v0
	v_fmac_f32_e32 v11, v28, v0
	v_fmac_f32_e32 v12, v29, v0
	v_fmac_f32_e32 v16, v17, v0
	v_lshlrev_b32_e32 v17, 16, v48
	v_and_b32_e32 v18, 0xffff0000, v48
	v_lshlrev_b32_e32 v19, 16, v49
	v_and_b32_e32 v20, 0xffff0000, v49
	v_cvt_pk_bf16_f32 v244, v9, v10
	v_cvt_pk_bf16_f32 v245, v11, v12
	s_nop 0
	s_nop 0
	v_cvt_pk_bf16_f32 v238, v13, v14
	v_cvt_pk_bf16_f32 v239, v15, v16
	s_mov_b64 s[2:3], 0
	s_and_b64 vcc, exec, s[50:51]
	v_fmac_f32_e32 v17, v30, v0
	v_fmac_f32_e32 v18, v31, v0
	v_fmac_f32_e32 v19, v32, v0
	v_fmac_f32_e32 v20, v33, v0
	v_cvt_pk_bf16_f32 v246, v17, v18
	v_cvt_pk_bf16_f32 v247, v19, v20
	v_permlane32_swap_b32_e32 v236, v238
	v_permlane32_swap_b32_e32 v237, v239
	global_store_dwordx4 v[248:249], v[236:239], off offset:32
	s_nop 1
	v_permlane32_swap_b32_e32 v244, v246
	v_permlane32_swap_b32_e32 v245, v247
	global_store_dwordx4 v[248:249], v[244:247], off offset:96
	s_cbranch_vccnz .LBB0_622

.LBB0_650:
	v_lshl_add_u32 v72, v185, 1, v185
	v_lshl_add_u64 v[66:67], v[152:153], 1, s[14:15]
	v_lshlrev_b64 v[68:69], 11, v[146:147]
	v_ashrrev_i32_e32 v73, 31, v72
	v_lshl_add_u64 v[68:69], v[66:67], 0, v[68:69]
	v_lshlrev_b32_e32 v0, 3, v186
	v_lshl_add_u64 v[72:73], v[72:73], 1, s[12:13]
	v_lshl_add_u64 v[146:147], v[68:69], 0, v[0:1]
	v_lshl_add_u64 v[154:155], v[72:73], 0, v[154:155]
	global_load_dwordx2 v[68:69], v[146:147], off offset:64
	global_load_dwordx2 v[70:71], v[146:147], off offset:80
	global_load_dwordx2 v[74:75], v[146:147], off offset:96
	global_load_ushort v84, v[154:155], off offset:2818
	global_load_dwordx2 v[72:73], v[146:147], off
	global_load_dwordx2 v[76:77], v[146:147], off offset:16
	global_load_dwordx2 v[78:79], v[146:147], off offset:32
	v_add_co_u32_e32 v226, vcc, 0x10000, v146
	s_nop 1
	v_addc_co_u32_e32 v227, vcc, 0, v147, vcc
	v_lshl_add_u64 v[228:229], v[154:155], 0, s[20:21]
	v_and_b32_e32 v230, 32, v200
	v_lshrrev_b32_e32 v230, 2, v230
	v_mov_b32_e32 v231, 0
	v_lshl_add_u64 v[230:231], v[226:227], 0, v[230:231]
	global_load_dwordx4 v[206:209], v[230:231], off
	global_load_dwordx4 v[210:213], v[230:231], off offset:32
	global_load_dwordx4 v[214:217], v[230:231], off offset:64
	global_load_dwordx4 v[218:221], v[230:231], off offset:96
	global_load_ushort v224, v[228:229], off offset:2818
	v_and_b32_e32 v81, 64, v174
	v_xor_b32_e32 v80, 32, v174
	v_add_u32_e32 v81, 64, v81
	v_cmp_lt_i32_e32 vcc, v80, v81
	v_lshl_add_u64 v[152:153], v[154:155], 0, s[20:21]
	s_waitcnt vmcnt(3)
	v_lshlrev_b32_e32 v84, 16, v84
	v_cndmask_b32_e32 v80, v174, v80, vcc
	v_lshlrev_b32_e32 v166, 2, v80
	ds_bpermute_b32 v82, v166, v157
	global_load_dwordx2 v[80:81], v[146:147], off offset:48
	v_mul_f32_e32 v84, 0xbfb8aa3b, v84
	v_exp_f32_e32 v84, v84
	s_waitcnt vmcnt(3)
	v_lshlrev_b32_e32 v95, 16, v72
	s_waitcnt lgkmcnt(0)
	v_add_f32_e32 v82, v157, v82
	v_max_f32_e32 v85, 0xda24260, v82
	global_load_dwordx2 v[82:83], v[146:147], off offset:112
	v_add_f32_e32 v84, 1.0, v84
	v_div_scale_f32 v101, s[0:1], v84, v84, 1.0
	v_div_scale_f32 v86, s[0:1], v85, v85, 1.0
	v_rcp_f32_e32 v102, v101
	v_rcp_f32_e32 v87, v86
	v_div_scale_f32 v103, vcc, 1.0, v84, 1.0
	v_fma_f32 v104, -v101, v102, 1.0
	v_fma_f32 v89, -v86, v87, 1.0
	v_fmac_f32_e32 v102, v104, v102
	v_div_scale_f32 v88, s[2:3], 1.0, v85, 1.0
	v_fmac_f32_e32 v87, v89, v87
	v_mul_f32_e32 v104, v103, v102
	v_mul_f32_e32 v89, v88, v87
	v_fma_f32 v105, -v101, v104, v103
	v_fma_f32 v90, -v86, v89, v88
	v_fmac_f32_e32 v104, v105, v102
	v_fmac_f32_e32 v89, v90, v87
	v_fma_f32 v101, -v101, v104, v103
	v_fma_f32 v86, -v86, v89, v88
	v_div_fmas_f32 v101, v101, v102, v104
	s_mov_b64 vcc, s[2:3]
	v_div_fmas_f32 v86, v86, v87, v89
	v_div_fixup_f32 v84, v101, v84, 1.0
	v_div_fixup_f32 v85, v86, v85, 1.0
	v_lshlrev_b32_e32 v88, 16, v68
	v_and_b32_e32 v68, 0xffff0000, v68
	v_and_b32_e32 v72, 0xffff0000, v72
	v_lshlrev_b32_e32 v96, 16, v73
	v_and_b32_e32 v73, 0xffff0000, v73
	v_mul_f32_e32 v84, v85, v84
	v_lshlrev_b32_e32 v90, 16, v69
	v_and_b32_e32 v69, 0xffff0000, v69
	v_lshlrev_b32_e32 v91, 16, v70
	v_and_b32_e32 v70, 0xffff0000, v70
	s_waitcnt vmcnt(3)
	v_lshlrev_b32_e32 v97, 16, v76
	v_and_b32_e32 v76, 0xffff0000, v76
	v_lshlrev_b32_e32 v98, 16, v77
	v_and_b32_e32 v77, 0xffff0000, v77
	v_fmac_f32_e32 v95, v50, v84
	v_fmac_f32_e32 v72, v51, v84
	v_fmac_f32_e32 v96, v52, v84
	v_fmac_f32_e32 v73, v53, v84
	v_fmac_f32_e32 v88, v34, v84
	v_fmac_f32_e32 v68, v35, v84
	v_cvt_pk_bf16_f32 v232, v95, v72
	v_cvt_pk_bf16_f32 v233, v96, v73
	v_lshlrev_b32_e32 v92, 16, v71
	v_and_b32_e32 v71, 0xffff0000, v71
	s_waitcnt vmcnt(2)
	v_lshlrev_b32_e32 v99, 16, v78
	v_and_b32_e32 v78, 0xffff0000, v78
	v_lshlrev_b32_e32 v100, 16, v79
	v_and_b32_e32 v79, 0xffff0000, v79
	v_fmac_f32_e32 v90, v36, v84
	v_fmac_f32_e32 v69, v37, v84
	v_fmac_f32_e32 v97, v54, v84
	v_fmac_f32_e32 v76, v55, v84
	v_fmac_f32_e32 v98, v56, v84
	v_fmac_f32_e32 v77, v57, v84
	v_fmac_f32_e32 v91, v38, v84
	v_fmac_f32_e32 v70, v39, v84
	v_cvt_pk_bf16_f32 v240, v88, v68
	v_cvt_pk_bf16_f32 v241, v90, v69
	s_nop 0
	s_nop 0
	v_cvt_pk_bf16_f32 v234, v97, v76
	v_cvt_pk_bf16_f32 v235, v98, v77
	v_lshlrev_b32_e32 v93, 16, v74
	v_and_b32_e32 v74, 0xffff0000, v74
	v_lshlrev_b32_e32 v94, 16, v75
	v_and_b32_e32 v75, 0xffff0000, v75
	s_waitcnt vmcnt(1)
	v_lshlrev_b32_e32 v38, 16, v80
	v_and_b32_e32 v39, 0xffff0000, v80
	v_fmac_f32_e32 v92, v40, v84
	v_fmac_f32_e32 v71, v41, v84
	v_fmac_f32_e32 v99, v58, v84
	v_fmac_f32_e32 v78, v59, v84
	v_fmac_f32_e32 v100, v60, v84
	v_fmac_f32_e32 v79, v61, v84
	v_fmac_f32_e32 v38, v62, v84
	v_fmac_f32_e32 v39, v63, v84
	v_cvt_pk_bf16_f32 v242, v91, v70
	v_cvt_pk_bf16_f32 v243, v92, v71
	v_and_b32_e32 v248, 32, v200
	v_lshrrev_b32_e32 v248, 2, v248
	v_mov_b32_e32 v249, 0
	v_lshl_add_u64 v[248:249], v[146:147], 0, v[248:249]
	v_permlane32_swap_b32_e32 v232, v234
	v_permlane32_swap_b32_e32 v233, v235
	global_store_dwordx4 v[248:249], v[232:235], off
	s_nop 1
	v_permlane32_swap_b32_e32 v240, v242
	v_permlane32_swap_b32_e32 v241, v243
	global_store_dwordx4 v[248:249], v[240:243], off offset:64
	v_cvt_pk_bf16_f32 v236, v99, v78
	v_cvt_pk_bf16_f32 v237, v100, v79
	v_fmac_f32_e32 v93, v42, v84
	v_fmac_f32_e32 v74, v43, v84
	v_fmac_f32_e32 v94, v44, v84
	v_fmac_f32_e32 v75, v45, v84
	v_cvt_pk_bf16_f32 v244, v93, v74
	v_cvt_pk_bf16_f32 v245, v94, v75
	s_nop 0
	s_nop 0
	v_cvt_pk_bf16_f32 v238, v38, v39
	v_lshlrev_b64 v[38:39], 11, v[148:149]
	v_lshlrev_b32_e32 v40, 16, v81
	v_and_b32_e32 v41, 0xffff0000, v81
	v_lshl_add_u64 v[38:39], v[66:67], 0, v[38:39]
	v_fmac_f32_e32 v40, v64, v84
	v_fmac_f32_e32 v41, v65, v84
	s_waitcnt vmcnt(2)
	v_lshlrev_b32_e32 v42, 16, v82
	v_and_b32_e32 v43, 0xffff0000, v82
	v_lshlrev_b32_e32 v44, 16, v83
	v_and_b32_e32 v45, 0xffff0000, v83
	v_cvt_pk_bf16_f32 v239, v40, v41
	v_lshl_add_u64 v[148:149], v[38:39], 0, v[0:1]
	v_fmac_f32_e32 v42, v46, v84
	v_fmac_f32_e32 v43, v47, v84
	v_fmac_f32_e32 v44, v48, v84
	v_fmac_f32_e32 v45, v49, v84
	v_cvt_pk_bf16_f32 v246, v42, v43
	v_cvt_pk_bf16_f32 v247, v44, v45
	s_waitcnt vmcnt(2)
	v_permlane32_swap_b32_e32 v206, v208
	v_permlane32_swap_b32_e32 v207, v209
	v_permlane32_swap_b32_e32 v210, v212
	v_permlane32_swap_b32_e32 v211, v213
	v_permlane32_swap_b32_e32 v214, v216
	v_permlane32_swap_b32_e32 v215, v217
	v_permlane32_swap_b32_e32 v218, v220
	v_permlane32_swap_b32_e32 v219, v221
	v_mov_b64_e32 v[38:39], v[214:215]
	s_nop 0
	v_permlane32_swap_b32_e32 v236, v238
	v_permlane32_swap_b32_e32 v237, v239
	global_store_dwordx4 v[248:249], v[236:239], off offset:32
	v_permlane32_swap_b32_e32 v244, v246
	v_permlane32_swap_b32_e32 v245, v247
	global_store_dwordx4 v[248:249], v[244:247], off offset:96
	v_mov_b32_e32 v0, v224
	s_nop 0
	v_mov_b64_e32 v[34:35], v[206:207]
	v_mov_b64_e32 v[36:37], v[208:209]
	v_mov_b64_e32 v[40:41], v[216:217]
	v_mov_b64_e32 v[42:43], v[210:211]
	ds_bpermute_b32 v46, v166, v156
	v_mov_b64_e32 v[44:45], v[218:219]
	s_waitcnt lgkmcnt(0)
	v_add_f32_e32 v46, v156, v46
	v_max_f32_e32 v50, 0xda24260, v46
	v_div_scale_f32 v51, s[0:1], v50, v50, 1.0
	v_rcp_f32_e32 v52, v51
	v_div_scale_f32 v53, s[2:3], 1.0, v50, 1.0
	v_fma_f32 v48, -v51, v52, 1.0
	v_fmac_f32_e32 v52, v48, v52
	v_mul_f32_e32 v54, v53, v52
	v_fma_f32 v48, -v51, v54, v53
	v_fmac_f32_e32 v54, v48, v52
	v_mov_b64_e32 v[48:49], v[220:221]
	v_mov_b64_e32 v[46:47], v[212:213]
	v_fma_f32 v51, -v51, v54, v53
	s_nop 0
	v_lshlrev_b32_e32 v0, 16, v0
	v_mul_f32_e32 v0, 0xbfb8aa3b, v0
	v_exp_f32_e32 v0, v0
	v_lshlrev_b32_e32 v55, 16, v39
	v_and_b32_e32 v39, 0xffff0000, v39
	s_nop 0
	v_lshlrev_b32_e32 v60, 16, v36
	v_add_f32_e32 v0, 1.0, v0
	v_div_scale_f32 v58, s[0:1], v0, v0, 1.0
	v_rcp_f32_e32 v59, v58
	v_div_scale_f32 v61, vcc, 1.0, v0, 1.0
	v_lshlrev_b32_e32 v53, 16, v38
	v_fma_f32 v62, -v58, v59, 1.0
	v_fmac_f32_e32 v59, v62, v59
	v_mul_f32_e32 v62, v61, v59
	v_fma_f32 v63, -v58, v62, v61
	v_fmac_f32_e32 v62, v63, v59
	v_fma_f32 v58, -v58, v62, v61
	v_div_fmas_f32 v58, v58, v59, v62
	s_mov_b64 vcc, s[2:3]
	v_div_fmas_f32 v51, v51, v52, v54
	v_div_fixup_f32 v0, v58, v0, 1.0
	v_div_fixup_f32 v50, v51, v50, 1.0
	v_mul_f32_e32 v0, v50, v0
	v_fmac_f32_e32 v55, v20, v0
	v_fmac_f32_e32 v39, v21, v0
	v_fmac_f32_e32 v60, v6, v0
	v_and_b32_e32 v6, 0xffff0000, v36
	s_nop 0
	v_and_b32_e32 v20, 0xffff0000, v41
	s_nop 0
	v_lshlrev_b32_e32 v21, 16, v42
	v_fmac_f32_e32 v6, v7, v0
	v_lshlrev_b32_e32 v7, 16, v37
	v_fmac_f32_e32 v20, v25, v0
	v_fmac_f32_e32 v21, v10, v0
	v_and_b32_e32 v10, 0xffff0000, v42
	s_nop 0
	v_lshlrev_b32_e32 v25, 16, v46
	v_and_b32_e32 v38, 0xffff0000, v38
	v_lshlrev_b32_e32 v56, 16, v34
	v_and_b32_e32 v34, 0xffff0000, v34
	v_lshlrev_b32_e32 v57, 16, v35
	v_and_b32_e32 v35, 0xffff0000, v35
	v_fmac_f32_e32 v7, v8, v0
	v_and_b32_e32 v8, 0xffff0000, v37
	v_fmac_f32_e32 v10, v11, v0
	v_lshlrev_b32_e32 v11, 16, v43
	v_fmac_f32_e32 v25, v14, v0
	v_and_b32_e32 v14, 0xffff0000, v46
	s_add_i32 s0, s84, -8
	v_fmac_f32_e32 v56, v2, v0
	v_fmac_f32_e32 v34, v3, v0
	v_fmac_f32_e32 v57, v4, v0
	v_fmac_f32_e32 v35, v5, v0
	v_fmac_f32_e32 v53, v18, v0
	v_fmac_f32_e32 v38, v19, v0
	v_fmac_f32_e32 v8, v9, v0
	v_lshlrev_b32_e32 v9, 16, v40
	v_and_b32_e32 v18, 0xffff0000, v40
	v_lshlrev_b32_e32 v19, 16, v41
	v_fmac_f32_e32 v11, v12, v0
	v_and_b32_e32 v12, 0xffff0000, v43
	v_fmac_f32_e32 v14, v15, v0
	v_lshlrev_b32_e32 v15, 16, v47
	v_cvt_pk_bf16_f32 v232, v56, v34
	v_cvt_pk_bf16_f32 v233, v57, v35
	v_cvt_pk_bf16_f32 v240, v53, v38
	v_cvt_pk_bf16_f32 v241, v55, v39
	s_cmp_gt_u32 s61, 1
	v_fmac_f32_e32 v9, v22, v0
	v_fmac_f32_e32 v18, v23, v0
	v_fmac_f32_e32 v19, v24, v0
	v_fmac_f32_e32 v12, v13, v0
	v_lshlrev_b32_e32 v13, 16, v44
	v_and_b32_e32 v22, 0xffff0000, v44
	v_lshlrev_b32_e32 v23, 16, v45
	v_and_b32_e32 v24, 0xffff0000, v45
	v_fmac_f32_e32 v15, v16, v0
	v_and_b32_e32 v16, 0xffff0000, v47
	s_nop 0
	s_nop 0
	v_cvt_pk_bf16_f32 v234, v60, v6
	v_cvt_pk_bf16_f32 v235, v7, v8
	v_cvt_pk_bf16_f32 v242, v9, v18
	v_cvt_pk_bf16_f32 v243, v19, v20
	s_cselect_b32 s85, s0, 0
	v_fmac_f32_e32 v13, v26, v0
	v_fmac_f32_e32 v22, v27, v0
	v_fmac_f32_e32 v23, v28, v0
	v_fmac_f32_e32 v24, v29, v0
	v_fmac_f32_e32 v16, v17, v0
	v_lshlrev_b32_e32 v17, 16, v48
	v_and_b32_e32 v26, 0xffff0000, v48
	v_lshlrev_b32_e32 v27, 16, v49
	v_and_b32_e32 v28, 0xffff0000, v49
	v_and_b32_e32 v248, 32, v200
	v_lshrrev_b32_e32 v248, 2, v248
	v_mov_b32_e32 v249, 0
	v_lshl_add_u64 v[248:249], v[148:149], 0, v[248:249]
	v_permlane32_swap_b32_e32 v232, v234
	v_permlane32_swap_b32_e32 v233, v235
	global_store_dwordx4 v[248:249], v[232:235], off
	v_permlane32_swap_b32_e32 v240, v242
	v_permlane32_swap_b32_e32 v241, v243
	global_store_dwordx4 v[248:249], v[240:243], off offset:64
	v_cvt_pk_bf16_f32 v236, v21, v10
	v_cvt_pk_bf16_f32 v237, v11, v12
	v_cvt_pk_bf16_f32 v244, v13, v22
	v_cvt_pk_bf16_f32 v245, v23, v24
	s_cmp_gt_u32 s85, s84
	v_fmac_f32_e32 v17, v30, v0
	v_fmac_f32_e32 v26, v31, v0
	v_fmac_f32_e32 v27, v32, v0
	v_fmac_f32_e32 v28, v33, v0
	s_nop 0
	s_nop 0
	v_cvt_pk_bf16_f32 v238, v25, v14
	v_cvt_pk_bf16_f32 v239, v15, v16
	v_cvt_pk_bf16_f32 v246, v17, v26
	v_cvt_pk_bf16_f32 v247, v27, v28
	v_permlane32_swap_b32_e32 v236, v238
	v_permlane32_swap_b32_e32 v237, v239
	global_store_dwordx4 v[248:249], v[236:239], off offset:32
	s_nop 1
	v_permlane32_swap_b32_e32 v244, v246
	v_permlane32_swap_b32_e32 v245, v247
	global_store_dwordx4 v[248:249], v[244:247], off offset:96
	s_cbranch_scc1 .LBB0_624
	s_lshl_b32 s84, s85, 6
	v_add_u32_e32 v0, s84, v183
	v_med3_i32 v0, v0, 0, v141
	v_mul_u32_u24_e32 v0, 0x600, v0
	v_lshl_add_u64 v[2:3], v[0:1], 1, s[44:45]
	v_lshlrev_b32_e32 v0, 1, v150
	v_lshl_add_u64 v[2:3], v[2:3], 0, v[0:1]
	global_load_dwordx4 v[18:21], v[2:3], off offset:2048
	global_load_dwordx4 v[22:25], v[2:3], off offset:2176
	s_add_i32 s60, s60, -11
	v_add3_u32 v0, s60, v181, v151
	v_sub_u32_e32 v0, v0, v184
	s_barrier
	v_mov_b32_e32 v16, v1
	v_mov_b32_e32 v17, v1
	v_mov_b32_e32 v2, v1
	v_mov_b32_e32 v3, v1
	v_mov_b32_e32 v4, v1
	v_mov_b32_e32 v5, v1
	v_mov_b32_e32 v6, v1
	v_mov_b32_e32 v7, v1
	v_mov_b32_e32 v8, v1
	v_mov_b32_e32 v9, v1
	v_mov_b32_e32 v10, v1
	v_mov_b32_e32 v11, v1
	v_mov_b32_e32 v12, v1
	v_mov_b32_e32 v13, v1
	v_mov_b32_e32 v14, v1
	v_mov_b32_e32 v15, v1
	v_subrev_u32_e32 v181, s84, v0
	v_mov_b32_e32 v0, v1
	v_mov_b64_e32 v[48:49], v[16:17]
	v_mov_b64_e32 v[64:65], v[16:17]
	s_mov_b32 s86, 0
	v_add_u32_e32 v167, 0xffffff80, v182
	v_add_u32_e32 v168, 0xfffffe01, v182
	v_add_u32_e32 v169, 0xfffffe21, v182
	v_add_u32_e32 v183, 0xfffffe40, v182
	v_add_u32_e32 v185, 0xfffffe20, v182
	v_add_u32_e32 v182, 0xffffffa0, v182
	v_mov_b32_e32 v186, 0xf149f2ca
	v_mov_b64_e32 v[46:47], v[14:15]
	v_mov_b64_e32 v[44:45], v[12:13]
	v_mov_b64_e32 v[42:43], v[10:11]
	v_mov_b64_e32 v[40:41], v[8:9]
	v_mov_b64_e32 v[38:39], v[6:7]
	v_mov_b64_e32 v[36:37], v[4:5]
	v_mov_b64_e32 v[34:35], v[2:3]
	v_mov_b64_e32 v[62:63], v[14:15]
	v_mov_b64_e32 v[60:61], v[12:13]
	v_mov_b64_e32 v[58:59], v[10:11]
	v_mov_b64_e32 v[56:57], v[8:9]
	v_mov_b64_e32 v[54:55], v[6:7]
	v_mov_b64_e32 v[52:53], v[4:5]
	v_mov_b64_e32 v[50:51], v[2:3]
	v_mov_b32_e32 v187, 0xf149f2ca
	v_mov_b64_e32 v[150:151], v[0:1]
	s_waitcnt vmcnt(1)
	ds_write_b128 v140, v[18:21]
	s_waitcnt vmcnt(0)
	ds_write_b128 v142, v[22:25] offset:18432
	s_waitcnt lgkmcnt(0)
	s_barrier
	ds_read_b32 v184, v175 offset:43524
	v_mov_b64_e32 v[32:33], v[16:17]
	v_mov_b64_e32 v[30:31], v[14:15]
	v_mov_b64_e32 v[28:29], v[12:13]
	v_mov_b64_e32 v[26:27], v[10:11]
	v_mov_b64_e32 v[24:25], v[8:9]
	v_mov_b64_e32 v[22:23], v[6:7]
	v_mov_b64_e32 v[20:21], v[4:5]
	v_mov_b64_e32 v[18:19], v[2:3]
	s_branch .LBB0_653
